# FF1 (P7) column-tile sweep reversed so FF2 (P8) reads the most recently written u columns first; otherwise v18
# speedup vs baseline: 1.0051x; 1.0022x over previous
; #define LAS __attribute__((address_space(3)))
; __device__ __forceinline__ unsigned xb_ld(unsigned* p)              { return __hip_atomic_load(p, __ATOMIC_RELAXED, __HIP_MEMORY_SCOPE_AGENT); }
; __device__ __forceinline__ void xcd_barrier_complete(unsigned* bar, unsigned x, unsigned& nloc, unsigned& nx) {
;     ...
;         sum = 0u; cnt = 0u; mine = 0u;
; #pragma unroll
;         for (unsigned j = 0; j < 16; ++j) { const unsigned c = xb_ld(&bar[XB_XCNT(j)]); sum += c; cnt += (c > 0u) ? 1u : 0u; mine = (j == x) ? c : mine; }
;         if (sum == G) break;
; __global__ void __launch_bounds__(NTHR, 2) fwd_megakernel(Args args) {
;     ...
;     const int tid0 = threadIdx.x, wave = __builtin_amdgcn_readfirstlane(tid0 >> 6);
;     ...
;     const int G = gridDim.x, bid = blockIdx.x, gw = bid * NWAVES + wave, NGW = G * NWAVES;
;     unsigned char* ws = args.ws;
;     float* rn2 = (float*)(ws + WS_RN2);
;     float* logf = (float*)(ws + WS_LOGF); float* cs = (float*)(ws + WS_CS);
;     bf16* Win_t = (bf16*)(ws + WS_WIN); bf16* Wc_t = (bf16*)(ws + WS_WC); bf16* Wa_t = (bf16*)(ws + WS_WA); bf16* Wmix_t = (bf16*)(ws + WS_WMIX);
;     bf16* W1_t = (bf16*)(ws + WS_W1); bf16* W2_t = (bf16*)(ws + WS_W2);
;     bf16* Z = (bf16*)(ws + WS_Z); bf16* XN = (bf16*)(ws + WS_XN); bf16* CONVY = (bf16*)(ws + WS_CONVY); bf16* ATTO = (bf16*)(ws + WS_ATTO);
;     bf16* XG = (bf16*)(ws + WS_Z + 256 * MiB);
;     float* rowss = (float*)(ws + WS_RSS);
;     float* xres = args.out;
;     volatile LAS unsigned* bst = (volatile LAS unsigned*)(L + att::LDS_BYTES + 65536 + 64);
;     if (tid0 < 2) bst[tid0] = 0u;
;     __syncthreads();
;     const XcdBarrier xbar = xcd_barrier_post((unsigned*)(ws + WS_BAR), bst);
.LBB0_5:
	s_or_b64 exec, exec, s[0:1]
	s_lshr_b32 s97, s6, 6
	s_lshl_b32 s0, s2, 3
	s_add_i32 s24, s97, s0
	s_lshl_b32 s80, s70, 3
	s_add_u32 s88, s68, 0x24000000
	s_addc_u32 s89, s69, 0
	s_add_u32 s18, s68, 0x100000
	s_addc_u32 s19, s69, 0
	s_add_u32 s20, s68, 0x180000
	s_addc_u32 s21, s69, 0
	s_add_u32 s26, s68, 0x200000
	s_addc_u32 s27, s69, 0
	s_add_u32 s28, s68, 0x2a00000
	s_addc_u32 s29, s69, 0
	s_add_u32 s30, s68, 0x2e00000
	s_addc_u32 s31, s69, 0
	s_add_u32 s34, s68, 0x3200000
	s_addc_u32 s35, s69, 0
	s_add_u32 s36, s68, 0x3a00000
	s_addc_u32 s37, s69, 0
	s_add_u32 s38, s68, 0x5a00000
	s_addc_u32 s39, s69, 0
	s_add_u32 s4, s68, 0x8000000
	s_addc_u32 s5, s69, 0
	s_add_u32 s6, s68, 0x1c000000
	s_addc_u32 s7, s69, 0
	s_add_u32 s8, s68, 0x20000000
	s_addc_u32 s9, s69, 0
	s_add_u32 s42, s68, 0x22000000
	s_addc_u32 s43, s69, 0
	s_add_u32 s10, s68, 0x18000000
	s_addc_u32 s11, s69, 0
	s_add_u32 s12, s68, 0x20000
	s_addc_u32 s13, s69, 0
	s_cmpk_lt_i32 s2, 0x100
	s_cselect_b64 s[0:1], -1, 0
	v_writelane_b32 v252, s0, 26
	v_lshrrev_b32_e32 v1, 20, v0
	v_lshrrev_b32_e32 v0, 10, v0
	v_writelane_b32 v252, s1, 27
	s_lshl_b32 s0, s97, 14
	s_add_i32 s0, s0, 0
	s_cmpk_lt_i32 s24, 0x7800
	v_writelane_b32 v252, s0, 28
	s_cselect_b64 s[0:1], -1, 0
	v_writelane_b32 v252, s0, 29
	s_ashr_i32 s25, s24, 31
	v_or_b32_e32 v0, v0, v1
	v_writelane_b32 v252, s1, 30
	s_lshl_b64 s[0:1], s[24:25], 13
	v_writelane_b32 v252, s0, 31
	s_cmpk_lt_i32 s24, 0x4000
	s_mul_i32 s71, s71, s70
	v_writelane_b32 v252, s1, 32
	s_cselect_b64 s[0:1], -1, 0
	v_writelane_b32 v252, s0, 33
	s_mul_i32 s71, s71, s16
	v_mbcnt_lo_u32_b32 v1, -1, 0
	v_writelane_b32 v252, s1, 34
	s_add_u32 s0, s68, 0x4200
	s_addc_u32 s1, s69, 0
	v_writelane_b32 v252, s0, 35
	v_mov_b32_e32 v193, 0
	v_mov_b32_e32 v237, 0x358637bd
	v_writelane_b32 v252, s1, 36
	s_add_u32 s0, s68, 0x4400
	s_addc_u32 s1, s69, 0
	v_writelane_b32 v252, s0, 37
	v_mov_b32_e32 v206, 0x260
	v_mbcnt_hi_u32_b32 v203, -1, v1
	v_writelane_b32 v252, s1, 38
	s_add_u32 s0, s68, 0x4500
	s_addc_u32 s1, s69, 0
	v_writelane_b32 v252, s0, 39
	v_mov_b32_e32 v207, 0xff800000
	v_mov_b32_e32 v208, 0x5000
	v_writelane_b32 v252, s1, 40
	s_add_u32 s0, s68, 0x4600
	s_addc_u32 s1, s69, 0
	v_writelane_b32 v252, s0, 41
	v_mov_b64_e32 v[232:233], 0x200
	v_mov_b64_e32 v[204:205], 0x1ff
	v_writelane_b32 v252, s1, 42
	s_add_u32 s0, s68, 0x4700
	s_addc_u32 s1, s69, 0
	v_writelane_b32 v252, s0, 43
	v_mov_b64_e32 v[250:251], 0x7ff
	s_movk_i32 s61, 0x4000
	v_writelane_b32 v252, s1, 44
	s_add_u32 s0, s68, 0x4800
	s_addc_u32 s1, s69, 0
	v_writelane_b32 v252, s0, 45
	s_movk_i32 s81, 0x7fff
	s_mov_b32 s96, 0xffff0000
	v_writelane_b32 v252, s1, 46
	s_add_u32 s0, s68, 0x4900
	s_addc_u32 s1, s69, 0
	v_writelane_b32 v252, s0, 47
	s_movk_i32 s84, 0x1000
	s_movk_i32 s85, 0x5000
	v_writelane_b32 v252, s1, 48
	s_add_u32 s0, s68, 0x4a00
	s_addc_u32 s1, s69, 0
	v_writelane_b32 v252, s0, 49
	s_mov_b32 s90, 0x42000000
	s_mov_b32 s60, 0x3e0293ee
	v_writelane_b32 v252, s1, 50
	s_add_u32 s0, s68, 0x4b00
	s_addc_u32 s1, s69, 0
	v_writelane_b32 v252, s0, 51
	s_nop 1
	v_writelane_b32 v252, s1, 52
	s_add_u32 s0, s68, 0x4c00
	s_addc_u32 s1, s69, 0
	v_writelane_b32 v252, s0, 53
	s_nop 1
	v_writelane_b32 v252, s1, 54
	s_add_u32 s0, s68, 0x4d00
	s_addc_u32 s1, s69, 0
	s_add_u32 s82, s68, 0x4e00
	v_writelane_b32 v252, s0, 55
	s_addc_u32 s83, s69, 0
	s_nop 0
	v_writelane_b32 v252, s1, 56
	s_add_u32 s0, s68, 0x4f00
	s_addc_u32 s1, s69, 0
	s_add_u32 s72, s68, 0x5000
	s_addc_u32 s73, s69, 0
	s_add_u32 s74, s68, 0x5100
	s_addc_u32 s75, s69, 0
	s_add_u32 s76, s68, 0x5200
	s_addc_u32 s77, s69, 0
	s_add_u32 s78, s68, 0x5300
	s_addc_u32 s79, s69, 0
	s_cmp_eq_u32 s3, 15
	s_cselect_b64 s[22:23], -1, 0
	v_writelane_b32 v252, s22, 57
	s_cmp_eq_u32 s3, 14
	s_nop 0
	v_writelane_b32 v252, s23, 58
	s_cselect_b64 s[22:23], -1, 0
	v_writelane_b32 v252, s22, 59
	s_cmp_eq_u32 s3, 13
	s_nop 0
	v_writelane_b32 v252, s23, 60
	s_cselect_b64 s[22:23], -1, 0
	v_writelane_b32 v252, s22, 61
	s_cmp_eq_u32 s3, 12
	s_nop 0
	v_writelane_b32 v252, s23, 62
	s_cselect_b64 s[22:23], -1, 0
	v_writelane_b32 v252, s22, 63
	s_cmp_eq_u32 s3, 11
	s_nop 0
	v_writelane_b32 v253, s23, 0
	s_cselect_b64 s[22:23], -1, 0
	v_writelane_b32 v253, s22, 1
	s_cmp_eq_u32 s3, 10
	s_nop 0
	v_writelane_b32 v253, s23, 2
	s_cselect_b64 s[22:23], -1, 0
	v_writelane_b32 v253, s22, 3
	s_cmp_eq_u32 s3, 9
	s_nop 0
	v_writelane_b32 v253, s23, 4
	s_cselect_b64 s[22:23], -1, 0
	v_writelane_b32 v253, s22, 5
	s_cmp_eq_u32 s3, 8
	s_nop 0
	v_writelane_b32 v253, s23, 6
	s_cselect_b64 s[22:23], -1, 0
	v_writelane_b32 v253, s22, 7
	s_cmp_eq_u32 s3, 7
	s_nop 0
	v_writelane_b32 v253, s23, 8
	s_cselect_b64 s[22:23], -1, 0
	v_writelane_b32 v253, s22, 9
	s_cmp_eq_u32 s3, 6
	s_nop 0
	v_writelane_b32 v253, s23, 10
	s_cselect_b64 s[22:23], -1, 0
	v_writelane_b32 v253, s22, 11
	s_cmp_eq_u32 s3, 5
	s_nop 0
	v_writelane_b32 v253, s23, 12
	s_cselect_b64 s[22:23], -1, 0
	v_writelane_b32 v253, s22, 13
	s_cmp_eq_u32 s3, 4
	s_nop 0
	v_writelane_b32 v253, s23, 14
	s_cselect_b64 s[22:23], -1, 0
	v_writelane_b32 v253, s22, 15
	s_cmp_eq_u32 s3, 3
	s_nop 0
	v_writelane_b32 v253, s23, 16
	s_cselect_b64 s[22:23], -1, 0
	v_writelane_b32 v253, s22, 17
	s_cmp_eq_u32 s3, 2
	s_nop 0
	v_writelane_b32 v253, s23, 18
	s_cselect_b64 s[22:23], -1, 0
	v_writelane_b32 v253, s22, 19
	s_cmp_eq_u32 s3, 1
	s_nop 0
	v_writelane_b32 v253, s23, 20
	s_cselect_b64 s[22:23], -1, 0
	v_writelane_b32 v253, s22, 21
	s_cmp_eq_u32 s3, 0
	s_nop 0
	v_writelane_b32 v253, s23, 22
	s_cselect_b64 s[22:23], -1, 0
	s_lshl_b32 s3, s17, 2
	s_add_u32 s3, s14, s3
	v_writelane_b32 v253, s22, 23
	s_addc_u32 s14, s15, 0
	s_nop 0
;     __host__ __device__ bool next(int i, Unit& u) const {
;         const long L = (long)i * G + c; if (L >= nwg) return false;
;         int wgid = (int)L; { const int q = nwg / NXCD, r = nwg % NXCD, xcd = wgid % NXCD, off = wgid / NXCD; wgid = (xcd < r ? xcd * (q + 1) : r * (q + 1) + (xcd - r) * q) + off; }
;         const int nig = WGM * nN, gid = wgid / nig, fm = gid * WGM, gsz = (nM - fm) < WGM ? (nM - fm) : WGM;
;         u.pm = fm + ((wgid % nig) % gsz); u.pn = (wgid % nig) / gsz; return true;
; __global__ void __launch_bounds__(NTHR, 2) fwd_megakernel(Args args) {
;     ...
;             const abf* Qb = (const abf*)Z + 3 * CWD; const abf* Kb = (const abf*)Z + 4 * CWD;
;             constexpr int NQB = S / att::QB, NITEM = NH * (NQB / 2);
;             unsigned ord = 0u;
;             {   float ce[NH];
; #pragma unroll
;                 for (int h = 0; h < NH; ++h) ce[h] = cs[(size_t)h * S + S - 1];
	v_writelane_b32 v253, s23, 24
	s_add_u32 s22, s3, 0x1400
	s_addc_u32 s23, s14, 0
	v_writelane_b32 v253, s22, 25
	s_nop 1
	v_writelane_b32 v253, s23, 26
	s_add_u32 s22, s3, 0x2400
	s_addc_u32 s23, s14, 0
	v_writelane_b32 v253, s22, 27
	s_add_u32 s14, s68, 0x7400
	s_addc_u32 s15, s69, 0
	v_writelane_b32 v253, s23, 28
	v_writelane_b32 v253, s14, 29
	s_nop 1
	v_writelane_b32 v253, s15, 30
	s_add_u32 s14, s68, 0x7500
	s_addc_u32 s15, s69, 0
	v_writelane_b32 v253, s14, 31
	s_cmp_lt_i32 s2, 8
	s_nop 0
	v_writelane_b32 v253, s15, 32
	s_cselect_b64 s[14:15], -1, 0
	v_writelane_b32 v253, s14, 33
	s_ashr_i32 s3, s2, 31
	s_nop 0
	v_writelane_b32 v253, s15, 34
	s_lshl_b64 s[14:15], s[2:3], 2
	s_add_u32 s14, s18, s14
	v_writelane_b32 v253, s18, 35
	s_addc_u32 s15, s19, s15
	s_nop 0
	v_writelane_b32 v253, s19, 36
	v_writelane_b32 v253, s14, 37
	s_nop 1
	v_writelane_b32 v253, s15, 38
	s_lshl_b64 s[14:15], s[2:3], 16
	v_writelane_b32 v253, s20, 39
	s_add_u32 s14, s20, s14
	v_writelane_b32 v253, s21, 40
	s_addc_u32 s15, s21, s15
	v_writelane_b32 v253, s14, 41
	s_cmpk_lt_i32 s2, 0xa00
	s_nop 0
	v_writelane_b32 v253, s15, 42
	s_cselect_b64 s[14:15], -1, 0
	v_writelane_b32 v253, s14, 43
	s_ashr_i32 s33, s70, 31
	s_nop 0
	v_writelane_b32 v253, s15, 44
	s_lshr_b32 s14, s3, 29
	s_add_i32 s14, s2, s14
	s_ashr_i32 s15, s14, 3
	s_and_b32 s14, s14, -8
	s_sub_i32 s14, s2, s14
	s_add_u32 s17, s68, 0x8001800
	v_writelane_b32 v253, s17, 45
	s_addc_u32 s17, s69, 0
	v_writelane_b32 v253, s17, 46
	s_add_u32 s17, s68, 0x8002000
	v_writelane_b32 v253, s17, 47
	s_addc_u32 s17, s69, 0
	v_writelane_b32 v253, s17, 48
	s_add_u32 s17, s68, 0x8000
	v_writelane_b32 v253, s17, 49
	s_addc_u32 s17, s69, 0
	v_writelane_b32 v253, s17, 50
	s_ashr_i32 s17, s70, 3
	s_mul_i32 s17, s17, s14
	s_add_i32 s17, s17, s15
	s_and_b32 s18, s70, 7
	s_add_u32 s20, s68, 0x8003000
	s_addc_u32 s21, s69, 0
	v_writelane_b32 v253, s20, 51
	s_cmpk_lt_i32 s2, 0x200
	s_nop 0
	v_writelane_b32 v253, s21, 52
	s_cselect_b64 s[20:21], -1, 0
	v_writelane_b32 v253, s20, 53
	s_lshl_b32 s19, s14, 6
	s_nop 0
	v_writelane_b32 v253, s21, 54
	s_add_u32 s20, s68, 0x8004000
	s_addc_u32 s21, s69, 0
	v_writelane_b32 v253, s20, 55
	s_cmpk_lt_i32 s2, 0x800
	s_nop 0
	v_writelane_b32 v253, s21, 56
	s_cselect_b64 s[20:21], -1, 0
	v_writelane_b32 v253, s20, 57
	s_nop 1
	v_writelane_b32 v253, s21, 58
	s_lshl_b32 s20, s14, 8
	s_cmp_lt_i32 s14, 0
	s_mul_i32 s21, s14, 0x41
	s_cselect_b32 s19, s21, s19
	s_movk_i32 s21, 0x141
	s_cselect_b32 s21, s21, 0x140
	s_mul_i32 s21, s14, s21
	s_mulk_i32 s14, 0x101
	s_cselect_b32 s22, s14, s20
	s_add_i32 s21, s21, s15
	s_mul_hi_i32 s14, s21, 0x66666667
	s_lshr_b32 s20, s14, 31
	s_ashr_i32 s14, s14, 7
	s_add_i32 s14, s14, s20
	s_mul_i32 s20, s14, 0x140
	s_sub_i32 s20, s21, s20
	s_lshr_b32 s21, s20, 3
	s_lshl_b32 s21, s21, 1
	s_mov_b32 s23, s21
	s_add_i32 s21, s21, 48
	s_cmpk_ge_i32 s21, 0x50
	s_cselect_b32 s23, 0x50, 0
	s_sub_i32 s21, s21, s23
	s_and_b32 s20, s20, 7
	s_lshl_b32 s14, s14, 3
	s_add_i32 s44, s14, s20
	s_ashr_i32 s14, s21, 1
	v_writelane_b32 v253, s14, 59
	s_lshr_b32 s14, s21, 1
	s_add_u32 s20, s68, 0x18fffc
	s_addc_u32 s21, s69, 0
	v_writelane_b32 v253, s20, 60
	s_nop 1
	v_writelane_b32 v253, s21, 61
	s_add_u32 s20, s68, 0x19fffc
	s_addc_u32 s21, s69, 0
	v_writelane_b32 v253, s20, 62
	s_nop 1
	v_writelane_b32 v253, s21, 63
	s_add_u32 s20, s68, 0x1afffc
	s_addc_u32 s21, s69, 0
	v_writelane_b32 v254, s20, 0
	s_nop 1
	v_writelane_b32 v254, s21, 1
	s_add_u32 s20, s68, 0x1bfffc
	s_addc_u32 s21, s69, 0
	v_writelane_b32 v254, s20, 2
	s_nop 1
	v_writelane_b32 v254, s21, 3
	s_add_u32 s20, s68, 0x1cfffc
	s_addc_u32 s21, s69, 0
	v_writelane_b32 v254, s20, 4
	s_nop 1
	v_writelane_b32 v254, s21, 5
	s_add_u32 s20, s68, 0x1dfffc
	s_addc_u32 s21, s69, 0
	v_writelane_b32 v254, s20, 6
	s_nop 1
	v_writelane_b32 v254, s21, 7
	s_add_u32 s20, s68, 0x1efffc
	s_addc_u32 s21, s69, 0
	v_writelane_b32 v254, s20, 8
	s_nop 1
	v_writelane_b32 v254, s21, 9
	s_add_u32 s20, s68, 0x1ffffc
	s_addc_u32 s21, s69, 0
	v_writelane_b32 v254, s20, 10
	s_cmp_eq_u32 s18, 0
	s_cselect_b32 s17, s17, s2
	v_writelane_b32 v254, s21, 11
	v_writelane_b32 v254, s17, 12
	s_add_i32 s17, s19, s15
	s_ashr_i32 s18, s17, 31
	s_lshr_b32 s18, s18, 28
	s_add_i32 s18, s17, s18
	s_and_b32 s19, s18, 0xfff0
	s_sub_i32 s17, s17, s19
	s_bfe_u32 s19, s17, 0x10007
	s_add_i32 s19, s17, s19
	s_and_b32 s20, s19, 0xfe
	s_sub_i32 s17, s17, s20
	s_ashr_i32 s18, s18, 4
	s_bfe_i32 s19, s19, 0x80000
	s_lshl_b32 s18, s18, 1
	s_sext_i32_i16 s19, s19
	s_sext_i32_i8 s17, s17
	s_add_i32 s46, s18, s17
	s_lshr_b32 s18, s19, 1
	s_ashr_i32 s47, s46, 31
	s_bfe_i64 s[40:41], s[18:19], 0x100000
	s_ashr_i32 s17, s19, 1
	s_lshl_b64 s[18:19], s[46:47], 19
	s_lshl_b64 s[20:21], s[40:41], 19
	v_writelane_b32 v254, s17, 13
	s_add_u32 s48, s28, s20
	v_writelane_b32 v254, s28, 14
	s_addc_u32 s49, s29, s21
	s_mov_b64 s[68:69], 0x80
	v_writelane_b32 v254, s29, 15
	s_add_u32 s28, s48, 0x40000
	s_addc_u32 s29, s49, 0
	v_writelane_b32 v254, s28, 16
	s_nop 1
	v_writelane_b32 v254, s29, 17
	s_add_u32 s28, s8, s18
	s_addc_u32 s29, s9, s19
	s_add_u32 s50, s28, 0x40000
	v_writelane_b32 v254, s28, 18
	s_addc_u32 s51, s29, 0
	s_nop 0
	v_writelane_b32 v254, s29, 19
	v_writelane_b32 v254, s50, 20
	s_add_u32 s28, s48, 0x40080
	s_nop 0
	v_writelane_b32 v254, s51, 21
	v_writelane_b32 v254, s48, 22
	s_addc_u32 s29, s49, 0
	s_add_u32 s20, s30, s20
	v_writelane_b32 v254, s49, 23
	v_writelane_b32 v254, s28, 24
	s_nop 1
	v_writelane_b32 v254, s29, 25
	v_writelane_b32 v254, s30, 26
	s_addc_u32 s21, s31, s21
	s_add_u32 s28, s20, 0x40000
	v_writelane_b32 v254, s31, 27
	s_addc_u32 s29, s21, 0
; #define PG8_WAIT_V(n) asm volatile("s_waitcnt vmcnt(" #n ")" ::: "memory")
; #define PG8_BAR __builtin_amdgcn_s_barrier()
;     __host__ __device__ bool next(int i, Unit& u) const {
;     ...
;         int wgid = (int)L; { const int q = nwg / NXCD, r = nwg % NXCD, xcd = wgid % NXCD, off = wgid / NXCD; wgid = (xcd < r ? xcd * (q + 1) : r * (q + 1) + (xcd - r) * q) + off; }
;         const int nig = WGM * nN, gid = wgid / nig, fm = gid * WGM, gsz = (nM - fm) < WGM ? (nM - fm) : WGM;
;         u.pm = fm + ((wgid % nig) % gsz); u.pn = (wgid % nig) / gsz; return true;
; template <class Epi, class Sched, bool ALIGN_EPI = false, bool SP2 = false>
; __device__ __forceinline__ void gemm_phase(PG8_LAS unsigned char* lds, const Gemm g, const Sched& S, const Epi& E) {
;     ...
;     const char* cA = (const char*)g.A + (size_t)cur.pm * tstepA; const char* cB = (const char*)g.Bt + (size_t)cur.pn * tstepB;
;     S.a_ready(cur);
;     if constexpr (SP2) {
;         PG8_STAGE(PG8_SB(0, 0), cB, voffB); PG8_STAGE(PG8_SB(0, 1), cB + hstepB, voffB); PG8_STAGE(PG8_SA(0, 0), cA, voffA); PG8_STAGE(PG8_SA(0, 1), cA + hstepA, voffA);
;         if (wr == 1) PG8_BAR;
;         PG8_WAIT_V(2); PG8_BAR;
;         PG8_STAGE(PG8_SB(1, 0), cB + kstep, voffB); PG8_STAGE(PG8_SA(1, 0), cA + kstep, voffA); PG8_STAGE(PG8_SB(1, 1), cB + hstepB + kstep, voffB);
;         PG8_WAIT_V(6); PG8_BAR;
;     } else {
;         PG8_STAGE(PG8_SB(0, 0), cB, voffB); PG8_STAGE(PG8_SA(0, 0), cA, voffA); PG8_STAGE(PG8_SB(0, 1), cB + hstepB, voffB); PG8_STAGE(PG8_SA(0, 1), cA + hstepA, voffA);
;         if (wr == 1) PG8_BAR;
;         PG8_WAIT_V(4); PG8_BAR;
;         PG8_STAGE(PG8_SB(1, 0), cB + kstep, voffB); PG8_STAGE(PG8_SA(1, 0), cA + kstep, voffA); PG8_STAGE(PG8_SB(1, 1), cB + hstepB + kstep, voffB);
;         PG8_WAIT_V(6); PG8_BAR;
;     }
;     for (;;) {
;         const bool has_next = S.next(ui + 1, nxt);
;         const char* nA = has_next ? (const char*)g.A + (size_t)nxt.pm * tstepA : cA; const char* nB = has_next ? (const char*)g.Bt + (size_t)nxt.pn * tstepB : cB;
;         for (int t = 0; t < nt; t += 2) {
;             const bool last = (t == nt - 2);
;             const char* a1 = cA + (size_t)(t + 1) * kstep;
;             const char* a2 = last ? nA : cA + (size_t)(t + 2) * kstep; const char* b2 = last ? nB : cB + (size_t)(t + 2) * kstep;
;             const char* a3 = a2 + kstep; const char* b3 = b2 + kstep;
	v_writelane_b32 v254, s28, 28
	s_add_u32 s18, s42, s18
	s_addc_u32 s19, s43, s19
	v_writelane_b32 v254, s29, 29
	v_writelane_b32 v254, s42, 30
	v_writelane_b32 v254, s43, 31
	s_add_u32 s28, s18, 0x40000
	v_writelane_b32 v254, s18, 32
	s_addc_u32 s29, s19, 0
	s_nop 0
	v_writelane_b32 v254, s19, 33
	v_writelane_b32 v254, s28, 34
	s_add_u32 s18, s20, 0x40080
	s_nop 0
	v_writelane_b32 v254, s29, 35
	v_writelane_b32 v254, s20, 36
	s_addc_u32 s19, s21, 0
	s_add_i32 s15, s22, s15
	s_ashr_i32 s17, s15, 31
	v_writelane_b32 v254, s21, 37
	s_lshr_b32 s17, s17, 24
	v_writelane_b32 v254, s18, 38
	s_add_i32 s17, s15, s17
	s_mov_b32 s28, s87
	v_writelane_b32 v254, s19, 39
	s_and_b32 s18, s17, 0xff00
	s_sub_i32 s15, s15, s18
	s_lshr_b32 s18, s15, 3
	s_lshl_b32 s18, s18, 1
	s_mov_b32 s19, s18
	s_sub_i32 s18, 62, s18
	s_and_b32 s15, s15, 7
	s_ashr_i32 s17, s17, 8
	s_nop 0
	s_lshl_b32 s17, s17, 3
	s_nop 0
	s_nop 0
	s_add_i32 s22, s17, s15
	s_ashr_i32 s15, s18, 1
	v_writelane_b32 v254, s15, 40
	s_lshr_b32 s18, s18, 1
	s_mov_b32 s20, s22
	s_ashr_i32 s23, s22, 31
	s_bfe_i64 s[18:19], s[18:19], 0x100000
	v_writelane_b32 v254, s20, 41
	s_lshl_b64 s[18:19], s[18:19], 20
	s_nop 0
	v_writelane_b32 v254, s21, 42
	s_lshl_b64 s[20:21], s[22:23], 20
	s_add_u32 s18, s36, s18
	s_addc_u32 s19, s37, s19
	s_add_u32 s22, s18, 0x80000
	s_addc_u32 s23, s19, 0
	v_writelane_b32 v254, s22, 43
	s_add_u32 s20, s10, s20
	s_addc_u32 s21, s11, s21
	v_writelane_b32 v254, s23, 44
	s_add_u32 s22, s20, 0x80000
	v_writelane_b32 v254, s20, 45
	s_addc_u32 s23, s21, 0
	s_nop 0
	v_writelane_b32 v254, s21, 46
	v_writelane_b32 v254, s22, 47
	s_add_u32 s20, s18, 0x80080
	s_nop 0
	v_writelane_b32 v254, s23, 48
	v_writelane_b32 v254, s18, 49
	s_addc_u32 s21, s19, 0
	s_nop 0
	v_writelane_b32 v254, s19, 50
	v_writelane_b32 v254, s20, 51
	s_lshl_b64 s[18:19], s[46:47], 22
	s_nop 0
	v_writelane_b32 v254, s21, 52
	s_lshl_b64 s[20:21], s[40:41], 22
	s_add_u32 s20, s38, s20
	v_writelane_b32 v254, s38, 53
	s_addc_u32 s21, s39, s21
	s_add_u32 s22, s20, 0x200000
	v_writelane_b32 v254, s39, 54
	s_addc_u32 s23, s21, 0
	v_writelane_b32 v254, s22, 55
	s_add_u32 s18, s4, s18
	s_addc_u32 s19, s5, s19
	v_writelane_b32 v254, s23, 56
	s_add_u32 s22, s18, 0x200000
	v_writelane_b32 v254, s18, 57
	s_addc_u32 s23, s19, 0
	s_movk_i32 s39, 0xbfff
	v_writelane_b32 v254, s19, 58
	v_writelane_b32 v254, s22, 59
	s_add_u32 s18, s20, 0x200080
	s_nop 0
	v_writelane_b32 v254, s23, 60
	v_writelane_b32 v254, s20, 61
	s_addc_u32 s19, s21, 0
	s_ashr_i32 s45, s44, 31
	v_writelane_b32 v254, s21, 62
	v_writelane_b32 v254, s18, 63
	s_bfe_i64 s[14:15], s[14:15], 0x100000
	s_lshl_b64 s[14:15], s[14:15], 20
	v_writelane_b32 v255, s19, 0
	s_mov_b32 s18, s44
	v_writelane_b32 v255, s18, 1
	s_nop 1
	v_writelane_b32 v255, s19, 2
	s_lshl_b64 s[18:19], s[44:45], 20
	s_add_u32 s14, s26, s14
	v_writelane_b32 v255, s26, 3
	s_addc_u32 s15, s27, s15
	s_add_u32 s20, s14, 0x80000
	v_writelane_b32 v255, s27, 4
	s_addc_u32 s21, s15, 0
	v_writelane_b32 v255, s20, 5
	s_add_u32 s18, s6, s18
	s_addc_u32 s19, s7, s19
	v_writelane_b32 v255, s21, 6
	s_add_u32 s20, s18, 0x80000
	v_writelane_b32 v255, s18, 7
	s_addc_u32 s21, s19, 0
	s_nop 0
	v_writelane_b32 v255, s19, 8
	v_writelane_b32 v255, s20, 9
	s_add_u32 s18, s14, 0x80080
	s_nop 0
	v_writelane_b32 v255, s21, 10
	v_writelane_b32 v255, s14, 11
	s_addc_u32 s19, s15, 0
	s_nop 0
	v_writelane_b32 v255, s15, 12
	v_writelane_b32 v255, s18, 13
	s_lshl_b64 s[14:15], s[40:41], 20
	s_nop 0
	v_writelane_b32 v255, s19, 14
	s_mov_b32 s18, s46
	v_writelane_b32 v255, s18, 15
	s_nop 1
	v_writelane_b32 v255, s19, 16
	s_lshl_b64 s[18:19], s[46:47], 20
	s_add_u32 s20, s34, s14
	v_writelane_b32 v255, s34, 17
	s_addc_u32 s21, s35, s15
	s_add_u32 s14, s20, 0x80000
	v_writelane_b32 v255, s35, 18
	s_addc_u32 s15, s21, 0
	v_writelane_b32 v255, s14, 19
	s_add_u32 s18, s6, s18
	s_addc_u32 s19, s7, s19
	v_writelane_b32 v255, s15, 20
	s_movk_i32 s14, 0x3ff
	v_and_or_b32 v0, v0, s14, v202
	s_add_u32 s14, s18, 0x80000
	v_writelane_b32 v255, s18, 21
	s_addc_u32 s15, s19, 0
	s_mov_b64 s[34:35], 0x2000
	v_writelane_b32 v255, s19, 22
	v_writelane_b32 v255, s14, 23
	s_nop 1
	v_writelane_b32 v255, s15, 24
	s_add_u32 s14, s20, 0x80080
	v_writelane_b32 v255, s20, 25
	s_addc_u32 s15, s21, 0
	s_nop 0
	v_writelane_b32 v255, s21, 26
	v_writelane_b32 v255, s14, 27
	s_nop 1
	v_writelane_b32 v255, s15, 28
	s_abs_i32 s14, s70
	s_sub_i32 s15, 1, s14
	s_cmp_lt_u32 s14, 2
	s_cselect_b32 s15, s15, 1
	s_sub_i32 s16, s15, s14
	s_cmp_ge_u32 s15, s14
	s_cselect_b32 s14, s16, s15
	s_cmp_eq_u32 s2, s14
	s_cselect_b64 s[14:15], -1, 0
	v_writelane_b32 v255, s14, 29
	s_lshl_b32 s22, s70, 10
	s_add_i32 s38, 0, 0x20808
	v_writelane_b32 v255, s15, 30
	s_lshl_b32 s14, s2, 8
	s_lshl_b32 s15, s97, 5
	s_add_i32 s14, s14, s15
	v_writelane_b32 v255, s14, 31
	s_lshl_b32 s14, s2, 10
	v_writelane_b32 v255, s14, 32
	s_lshl_b32 s14, s70, 8
	v_writelane_b32 v255, s14, 33
	s_add_i32 s14, s24, 0xa800
	v_writelane_b32 v255, s14, 34
	s_add_i32 s14, s24, 0xc800
	v_writelane_b32 v255, s14, 35
	s_add_i32 s14, s24, 0xd000
	v_writelane_b32 v255, s14, 36
	s_add_i32 s14, s24, 0xd400
	v_writelane_b32 v255, s14, 37
	s_mov_b32 s14, s24
	v_writelane_b32 v255, s14, 38
	s_nop 1
	v_writelane_b32 v255, s15, 39
	s_add_i32 s14, s24, 0xd800
	v_writelane_b32 v255, s14, 40
	s_add_i32 s14, 0, 0x20840
	v_writelane_b32 v255, s14, 41
	s_add_i32 s14, 0, 0x20844
	v_writelane_b32 v255, s14, 42
	s_add_i32 s14, 0, 0x20800
	v_writelane_b32 v255, s14, 43
	s_add_i32 s14, 0, 0x2080c
	v_writelane_b32 v255, s14, 44
	s_add_i32 s14, 0, 0x20804
	v_writelane_b32 v255, s14, 45
	v_cmp_eq_u32_e64 s[14:15], 0, v0
	s_nop 1
	v_writelane_b32 v255, s14, 46
	s_nop 1
	v_writelane_b32 v255, s15, 47
	v_writelane_b32 v255, s56, 48
	s_mov_b64 s[14:15], -1
	s_nop 0
	v_writelane_b32 v255, s57, 49
	v_writelane_b32 v255, s97, 50
	v_writelane_b32 v255, s36, 51
	s_nop 1
	v_writelane_b32 v255, s37, 52
	v_writelane_b32 v255, s22, 53
	s_branch .LBB0_8

;     __host__ __device__ bool next(int i, Unit& u) const {
;     ...
;         const int nig = WGM * nN, gid = wgid / nig, fm = gid * WGM, gsz = (nM - fm) < WGM ? (nM - fm) : WGM;
;         u.pm = fm + ((wgid % nig) % gsz); u.pn = (wgid % nig) / gsz; return true;
.LBB0_770:
	s_ashr_i32 s24, s24, 3
	s_add_i32 s24, s46, s24
	s_ashr_i32 s25, s24, 31
	s_lshr_b32 s25, s25, 24
	s_add_i32 s25, s24, s25
	s_ashr_i32 s26, s25, 8
	s_lshl_b32 s26, s26, 3
	s_sub_i32 s27, 64, s26
	s_min_i32 s27, s27, 8
	s_abs_i32 s28, s27
	v_cvt_f32_u32_e32 v0, s28
	s_sub_i32 s30, 0, s28
	s_andn2_b32 s25, s25, 255
	s_sub_i32 s24, s24, s25
	v_rcp_iflag_f32_e32 v0, v0
	s_abs_i32 s25, s24
	s_xor_b32 s29, s24, s27
	s_ashr_i32 s29, s29, 31
	v_mul_f32_e32 v0, 0x4f7ffffe, v0
	v_cvt_u32_f32_e32 v0, v0
	s_nop 0
	v_readfirstlane_b32 s31, v0
	s_mul_i32 s30, s30, s31
	s_mul_hi_u32 s30, s31, s30
	s_add_i32 s31, s31, s30
	s_mul_hi_u32 s30, s25, s31
	s_mul_i32 s31, s30, s28
	s_sub_i32 s25, s25, s31
	s_add_i32 s44, s30, 1
	s_sub_i32 s31, s25, s28
	s_cmp_ge_u32 s25, s28
	s_cselect_b32 s30, s44, s30
	s_cselect_b32 s25, s31, s25
	s_add_i32 s31, s30, 1
	s_cmp_ge_u32 s25, s28
	s_cselect_b32 s25, s31, s30
	s_xor_b32 s25, s25, s29
	s_sub_i32 s44, s25, s29
	s_mul_i32 s25, s44, s27
	s_sub_i32 s24, s24, s25
	s_add_i32 s46, s26, s24
	s_sub_i32 s44, 31, s44
